# combined + APP: prompt unit prologue tile-skip inputs and 4th K-row fragment issued with the unit's first loads
# baseline (speedup 1.0000x reference)
; #define LAS __attribute__((address_space(3)))
; __device__ __forceinline__ void attn_unit(const Args& a, LAS unsigned char* lds, const int mode, const int h, const int qb, const int tid_in, const int lane_in, const int wave) {
;     ...
;     { const float pfx = mode == 0 ? ((const float*)(ws + WS_PFXP))[h * 256 + (qrow >> 6)] : ((const float*)(ws + WS_PFXS))[qb * 16 + h];
;       cq2 = (pfx + CLT[qrow]) * L2E;
; #pragma unroll
;       for (int d0 = 0; d0 < 4; ++d0) qr[d0] = *(const bf16x8*)(Qb + (size_t)qrow * D + h * HD + d0 * 16 + hi * 8); }
;     ...
;         for (int d0 = 0; d0 < 4; ++d0) { const u32x4 kw = *(const u32x4*)(Kb + (size_t)qrow * D + h * HD + d0 * 16 + hi * 8); const u32x4 qw = __builtin_bit_cast(u32x4, qr[d0]);
;             const unsigned kk[4] = {kw.x, kw.y, kw.z, kw.w}; const unsigned qq[4] = {qw.x, qw.y, qw.z, qw.w};
; #pragma unroll
;             for (int e = 0; e < 4; ++e) dsc += __uint_as_float(kk[e] << 16) * __uint_as_float(qq[e] << 16) + __uint_as_float(kk[e] & 0xffff0000u) * __uint_as_float(qq[e] & 0xffff0000u); }
;         dsc += __shfl_xor(dsc, 32);
; #pragma unroll
;         for (int o = 1; o < 32; o <<= 1) dsc = fminf(dsc, __shfl_xor(dsc, o));
;         float qsq = 0.f;
; #pragma unroll
;         for (int d0 = 0; d0 < 4; ++d0) { const u32x4 qw = __builtin_bit_cast(u32x4, qr[d0]); const unsigned qq[4] = {qw.x, qw.y, qw.z, qw.w};
; #pragma unroll
;             for (int e = 0; e < 4; ++e) { const float lo = __uint_as_float(qq[e] << 16), hi_ = __uint_as_float(qq[e] & 0xffff0000u); qsq += lo * lo + hi_ * hi_; } }
;         qsq += __shfl_xor(qsq, 32);
; #pragma unroll
;         for (int o = 1; o < 32; o <<= 1) qsq = fmaxf(qsq, __shfl_xor(qsq, o));
;         LAS float* red = (LAS float*)(lds + AT_END);
;         if (lane == 0) { red[wave] = dsc; red[8 + wave] = qsq; }
;         __syncthreads();
;         float dmin = red[0], qn = red[8];
; #pragma unroll
;         for (int w = 1; w < 8; ++w) { dmin = fminf(dmin, red[w]); qn = fmaxf(qn, red[8 + w]); }
;         const float* N2 = (const float*)(ws + WS_N2); const float* PF = (const float*)(ws + WS_PFXP) + h * 256;
;         const float cq0 = (PF[qb * 4] + CLT[qb * 256]) * L2E, base = cq0 - dmin + 0.05f + 30.f;
;         int cnt = 0; bool open = true;
; #pragma unroll
;         for (int i = 0; i < 4; ++i) { const int j = lane + 64 * i; bool sk = false;
.LBB0_501:
	s_andn2_b64 vcc, exec, s[0:1]
	s_cbranch_vccnz .LBB0_542
	s_add_i32 s0, s68, 0xffffff00
	s_and_b32 s17, s68, 15
	s_lshr_b32 s0, s0, 4
	s_sub_i32 s1, 63, s0
	s_mul_i32 s2, s17, 0x11000
	v_readlane_b32 s3, v254, 28
	s_add_u32 s8, s3, s2
	v_readlane_b32 s2, v254, 30
	v_mov_b32_e32 v1, v134
	s_addc_u32 s9, s2, 0
	s_lshl_b32 s2, s1, 8
	v_readlane_b32 s3, v254, 25
	s_add_i32 s3, s2, s3
	v_and_b32_e32 v6, 31, v1
	v_or_b32_e32 v92, s3, v6
	s_lshl_b32 s15, s17, 8
	s_lshr_b32 s3, s3, 6
	v_mov_b32_e32 v93, v0
	v_readlane_b32 s4, v254, 26
	s_add_i32 s3, s3, s15
	v_lshlrev_b64 v[2:3], 11, v[92:93]
	v_readlane_b32 s5, v254, 27
	v_bfe_u32 v7, v1, 5, 1
	s_lshl_b32 s3, s3, 2
	v_lshl_add_u64 v[8:9], s[4:5], 0, v[2:3]
	s_lshl_b32 s72, s17, 7
	v_mov_b32_e32 v14, s3
	v_lshl_add_u64 v[8:9], v[8:9], 0, s[72:73]
	v_lshlrev_b32_e32 v10, 4, v7
	v_mov_b32_e32 v11, v0
	v_lshl_add_u64 v[4:5], v[92:93], 2, s[8:9]
	v_lshl_add_u64 v[12:13], v[8:9], 0, v[10:11]
	global_load_dword v9, v14, s[60:61]
	global_load_dword v10, v[4:5], off
	global_load_dwordx4 v[66:69], v[12:13], off
	global_load_dwordx4 v[70:73], v[12:13], off offset:32
	global_load_dwordx4 v[74:77], v[12:13], off offset:64
	global_load_dwordx4 v[78:81], v[12:13], off offset:96
	s_lshl_b32 s16, s1, 2
	s_lshl_b32 s14, s17, 6
	v_and_b32_e32 v8, 63, v1
	v_lshlrev_b32_e32 v90, 3, v7
	s_cmp_eq_u32 s0, 63
	s_mov_b32 s12, 0
	s_cbranch_scc1 .LBB0_514
	v_lshl_add_u64 v[2:3], s[38:39], 0, v[2:3]
	s_lshl_b32 s72, s14, 1
	v_lshl_add_u64 v[2:3], v[2:3], 0, s[72:73]
	v_lshlrev_b32_e32 v4, 1, v90
	v_mov_b32_e32 v5, v0
	v_lshl_add_u64 v[2:3], v[2:3], 0, v[4:5]
	global_load_dwordx4 v[16:19], v[2:3], off
	global_load_dwordx4 v[24:27], v[2:3], off offset:32
	global_load_dwordx4 v[32:35], v[2:3], off offset:64
	global_load_dwordx4 v[236:239], v[2:3], off offset:96
	s_lshl_b32 s100, s15, 2
	s_add_u32 s100, s60, s100
	s_addc_u32 s101, s61, 0
	s_lshl_b32 s99, s16, 2
	v_mov_b32_e32 v200, s99
	s_lshl_b32 s99, s2, 2
	v_mov_b32_e32 v201, s99
	v_lshlrev_b32_e32 v202, 2, v8
	global_load_dword v240, v200, s[100:101]
	global_load_dword v241, v201, s[8:9]
	global_load_dword v242, v202, s[100:101] offset:4
	global_load_dword v243, v202, s[100:101] offset:260
	global_load_dword v244, v202, s[100:101] offset:516
	global_load_dword v245, v202, s[100:101] offset:772
	s_lshl_b32 s99, s17, 2
	v_lshl_or_b32 v204, v8, 7, s99
	v_mov_b32_e32 v205, v0
	v_lshl_add_u64 v[204:205], s[88:89], 0, v[204:205]
	s_mov_b64 s[98:99], 0x191040
	v_lshl_add_u64 v[204:205], v[204:205], 0, s[98:99]
	s_mov_b64 s[98:99], 0x2000
	global_load_dword v246, v[204:205], off
	v_lshl_add_u64 v[204:205], v[204:205], 0, s[98:99]
	global_load_dword v247, v[204:205], off
	v_lshl_add_u64 v[204:205], v[204:205], 0, s[98:99]
	global_load_dword v248, v[204:205], off
	v_lshl_add_u64 v[204:205], v[204:205], 0, s[98:99]
	global_load_dword v249, v[204:205], off
	v_cmp_gt_u32_e64 s[98:99], 32, v138
	v_and_b32_e32 v253, 16, v138
	v_cmp_eq_u32_e64 s[100:101], 0, v253
	s_waitcnt vmcnt(17)
	v_and_b32_e32 v12, 0xffff0000, v66
	v_lshlrev_b32_e32 v11, 16, v66
	v_and_b32_e32 v15, 0xffff0000, v67
	v_lshlrev_b32_e32 v13, 16, v67
	s_waitcnt vmcnt(16)
	v_and_b32_e32 v21, 0xffff0000, v70
	v_and_b32_e32 v23, 0xffff0000, v71
	s_waitcnt vmcnt(15)
	v_and_b32_e32 v29, 0xffff0000, v74
	v_and_b32_e32 v31, 0xffff0000, v75
	s_waitcnt vmcnt(14)
	v_and_b32_e32 v38, 0xffff0000, v78
	v_lshlrev_b32_e32 v37, 16, v78
	v_and_b32_e32 v39, 0xffff0000, v79
	v_and_b32_e32 v40, 0xffff0000, v80
	v_and_b32_e32 v41, 0xffff0000, v81
	s_waitcnt vmcnt(13)
	v_and_b32_e32 v5, 0xffff0000, v16
	v_lshlrev_b32_e32 v4, 16, v16
	v_mul_f32_e32 v5, v12, v5
	v_fmac_f32_e32 v5, v11, v4
	v_and_b32_e32 v14, 0xffff0000, v17
	v_add_f32_e32 v4, 0, v5
	v_lshlrev_b32_e32 v5, 16, v17
	v_mul_f32_e32 v14, v15, v14
	v_fmac_f32_e32 v14, v13, v5
	v_and_b32_e32 v16, 0xffff0000, v18
	v_and_b32_e32 v17, 0xffff0000, v68
	v_add_f32_e32 v4, v14, v4
	v_lshlrev_b32_e32 v5, 16, v18
	v_lshlrev_b32_e32 v14, 16, v68
	v_mul_f32_e32 v16, v17, v16
	v_fmac_f32_e32 v16, v14, v5
	v_lshlrev_b32_e32 v5, 16, v19
	v_and_b32_e32 v19, 0xffff0000, v19
	v_and_b32_e32 v18, 0xffff0000, v69
	v_add_f32_e32 v4, v16, v4
	v_lshlrev_b32_e32 v16, 16, v69
	v_mul_f32_e32 v19, v18, v19
	v_fmac_f32_e32 v19, v16, v5
	s_waitcnt vmcnt(12)
	v_and_b32_e32 v20, 0xffff0000, v24
	v_add_f32_e32 v4, v19, v4
	v_lshlrev_b32_e32 v5, 16, v24
	v_lshlrev_b32_e32 v19, 16, v70
	v_mul_f32_e32 v20, v21, v20
	v_fmac_f32_e32 v20, v19, v5
	v_and_b32_e32 v22, 0xffff0000, v25
	v_add_f32_e32 v4, v20, v4
	v_lshlrev_b32_e32 v5, 16, v25
	v_lshlrev_b32_e32 v20, 16, v71
	v_mul_f32_e32 v22, v23, v22
	v_fmac_f32_e32 v22, v20, v5
	v_and_b32_e32 v24, 0xffff0000, v26
	v_and_b32_e32 v25, 0xffff0000, v72
	v_add_f32_e32 v4, v22, v4
	v_lshlrev_b32_e32 v5, 16, v26
	v_lshlrev_b32_e32 v22, 16, v72
	v_mul_f32_e32 v24, v25, v24
	v_fmac_f32_e32 v24, v22, v5
	v_lshlrev_b32_e32 v5, 16, v27
	v_and_b32_e32 v27, 0xffff0000, v27
	v_and_b32_e32 v26, 0xffff0000, v73
	v_add_f32_e32 v4, v24, v4
	v_lshlrev_b32_e32 v24, 16, v73
	v_mul_f32_e32 v27, v26, v27
	v_fmac_f32_e32 v27, v24, v5
	s_waitcnt vmcnt(11)
	v_and_b32_e32 v28, 0xffff0000, v32
	v_add_f32_e32 v4, v27, v4
	v_lshlrev_b32_e32 v5, 16, v32
	v_lshlrev_b32_e32 v27, 16, v74
	v_mul_f32_e32 v28, v29, v28
	v_fmac_f32_e32 v28, v27, v5
	v_and_b32_e32 v30, 0xffff0000, v33
	v_add_f32_e32 v4, v28, v4
	v_lshlrev_b32_e32 v5, 16, v33
	v_lshlrev_b32_e32 v28, 16, v75
	v_mul_f32_e32 v30, v31, v30
	v_fmac_f32_e32 v30, v28, v5
	v_and_b32_e32 v32, 0xffff0000, v34
	v_and_b32_e32 v33, 0xffff0000, v76
	v_add_f32_e32 v4, v30, v4
	v_lshlrev_b32_e32 v5, 16, v34
	v_lshlrev_b32_e32 v30, 16, v76
	v_mul_f32_e32 v32, v33, v32
	v_fmac_f32_e32 v32, v30, v5
	v_lshlrev_b32_e32 v5, 16, v35
	v_and_b32_e32 v35, 0xffff0000, v35
	v_and_b32_e32 v34, 0xffff0000, v77
	v_add_f32_e32 v4, v32, v4
	v_lshlrev_b32_e32 v32, 16, v77
	v_mul_f32_e32 v35, v34, v35
	v_fmac_f32_e32 v35, v32, v5
	v_add_f32_e32 v35, v35, v4
	s_waitcnt vmcnt(10)
; __device__ __forceinline__ void attn_unit(const Args& a, LAS unsigned char* lds, const int mode, const int h, const int qb, const int tid_in, const int lane_in, const int wave) {
;     ...
;         for (int d0 = 0; d0 < 4; ++d0) { const u32x4 kw = *(const u32x4*)(Kb + (size_t)qrow * D + h * HD + d0 * 16 + hi * 8); const u32x4 qw = __builtin_bit_cast(u32x4, qr[d0]);
;             const unsigned kk[4] = {kw.x, kw.y, kw.z, kw.w}; const unsigned qq[4] = {qw.x, qw.y, qw.z, qw.w};
; #pragma unroll
;             for (int e = 0; e < 4; ++e) dsc += __uint_as_float(kk[e] << 16) * __uint_as_float(qq[e] << 16) + __uint_as_float(kk[e] & 0xffff0000u) * __uint_as_float(qq[e] & 0xffff0000u); }
;         dsc += __shfl_xor(dsc, 32);
; #pragma unroll
;         for (int o = 1; o < 32; o <<= 1) dsc = fminf(dsc, __shfl_xor(dsc, o));
;         float qsq = 0.f;
; #pragma unroll
;         for (int d0 = 0; d0 < 4; ++d0) { const u32x4 qw = __builtin_bit_cast(u32x4, qr[d0]); const unsigned qq[4] = {qw.x, qw.y, qw.z, qw.w};
; #pragma unroll
;             for (int e = 0; e < 4; ++e) { const float lo = __uint_as_float(qq[e] << 16), hi_ = __uint_as_float(qq[e] & 0xffff0000u); qsq += lo * lo + hi_ * hi_; } }
;         qsq += __shfl_xor(qsq, 32);
; #pragma unroll
;         for (int o = 1; o < 32; o <<= 1) qsq = fmaxf(qsq, __shfl_xor(qsq, o));
	v_mov_b32_e32 v2, v236
	v_mov_b32_e32 v3, v237
	v_mov_b32_e32 v4, v238
	v_mov_b32_e32 v5, v239
	v_mul_f32_e32 v12, v12, v12
	v_fmac_f32_e32 v12, v11, v11
	v_mul_f32_e32 v11, v15, v15
	v_fmac_f32_e32 v11, v13, v13
	v_add_f32_e32 v11, v12, v11
	v_mul_f32_e32 v12, v17, v17
	v_fmac_f32_e32 v12, v14, v14
	v_add_f32_e32 v11, v12, v11
	v_mul_f32_e32 v12, v18, v18
	v_fmac_f32_e32 v12, v16, v16
	v_add_f32_e32 v11, v12, v11
	v_mul_f32_e32 v12, v21, v21
	v_fmac_f32_e32 v12, v19, v19
	v_add_f32_e32 v11, v12, v11
	v_mul_f32_e32 v12, v23, v23
	v_fmac_f32_e32 v12, v20, v20
	v_add_f32_e32 v11, v12, v11
	v_mul_f32_e32 v12, v25, v25
	v_fmac_f32_e32 v12, v22, v22
	v_add_f32_e32 v11, v12, v11
	v_mul_f32_e32 v12, v26, v26
	v_fmac_f32_e32 v12, v24, v24
	v_add_f32_e32 v11, v12, v11
	v_mul_f32_e32 v12, v29, v29
	v_fmac_f32_e32 v12, v27, v27
	v_add_f32_e32 v11, v12, v11
	v_mul_f32_e32 v12, v31, v31
	v_fmac_f32_e32 v12, v28, v28
	v_add_f32_e32 v11, v12, v11
	v_mul_f32_e32 v12, v33, v33
	v_fmac_f32_e32 v12, v30, v30
	v_add_f32_e32 v11, v12, v11
	v_mul_f32_e32 v12, v34, v34
	v_fmac_f32_e32 v12, v32, v32
	v_add_f32_e32 v11, v12, v11
	v_mul_f32_e32 v12, v38, v38
	v_fmac_f32_e32 v12, v37, v37
	v_add_f32_e32 v11, v12, v11
	v_mul_f32_e32 v12, v39, v39
	s_waitcnt vmcnt(0)
	v_lshlrev_b32_e32 v36, 16, v2
	v_and_b32_e32 v2, 0xffff0000, v2
	v_mul_f32_e32 v2, v38, v2
	v_fmac_f32_e32 v2, v37, v36
	v_add_f32_e32 v2, v2, v35
	v_lshlrev_b32_e32 v35, 16, v3
	v_and_b32_e32 v3, 0xffff0000, v3
	v_lshlrev_b32_e32 v36, 16, v79
	v_mul_f32_e32 v3, v39, v3
	v_fmac_f32_e32 v3, v36, v35
	v_add_f32_e32 v2, v3, v2
	v_lshlrev_b32_e32 v3, 16, v4
	v_and_b32_e32 v4, 0xffff0000, v4
	v_lshlrev_b32_e32 v35, 16, v80
	v_mul_f32_e32 v4, v40, v4
	v_fmac_f32_e32 v4, v35, v3
	v_lshlrev_b32_e32 v3, 16, v5
	v_and_b32_e32 v5, 0xffff0000, v5
	v_add_f32_e32 v2, v4, v2
	v_lshlrev_b32_e32 v4, 16, v81
	v_mul_f32_e32 v5, v41, v5
	v_fmac_f32_e32 v5, v4, v3
	v_add_f32_e32 v2, v5, v2
	v_and_b32_e32 v5, 64, v138
	v_xor_b32_e32 v3, 32, v138
	v_add_u32_e32 v5, 64, v5
	v_cmp_lt_i32_e32 vcc, v3, v5
	v_fmac_f32_e32 v12, v36, v36
	v_add_f32_e32 v11, v12, v11
	v_cndmask_b32_e32 v3, v138, v3, vcc
	v_lshlrev_b32_e32 v42, 2, v3
	v_mov_b32_e32 v3, v2
	v_mov_b32_e32 v253, v2
	s_nop 1
	v_permlane32_swap_b32_e32 v3, v253
	v_cndmask_b32_e64 v3, v3, v253, s[98:99]
	v_mul_f32_e32 v12, v40, v40
	v_fmac_f32_e32 v12, v35, v35
	v_add_f32_e32 v11, v12, v11
	v_mul_f32_e32 v12, v41, v41
	s_waitcnt lgkmcnt(0)
	v_add_f32_e32 v2, v2, v3
	v_xor_b32_e32 v3, 1, v138
	v_cmp_lt_i32_e32 vcc, v3, v5
	v_fmac_f32_e32 v12, v4, v4
	v_add_f32_e32 v4, v12, v11
	v_cndmask_b32_e32 v3, v138, v3, vcc
	v_lshlrev_b32_e32 v43, 2, v3
	s_nop 1
	v_mov_b32_dpp v3, v2 quad_perm:[1,0,3,2] row_mask:0xf bank_mask:0xf
	v_mov_b32_e32 v11, v4
	v_mov_b32_e32 v253, v4
	s_nop 1
	v_permlane32_swap_b32_e32 v11, v253
	v_cndmask_b32_e64 v11, v11, v253, s[98:99]
	s_waitcnt lgkmcnt(1)
	v_max_f32_e32 v3, v3, v3
	v_min_f32_e32 v2, v2, v3
	v_xor_b32_e32 v3, 2, v138
	v_cmp_lt_i32_e32 vcc, v3, v5
	s_waitcnt lgkmcnt(0)
	v_add_f32_e32 v4, v4, v11
	s_nop 1
	v_mov_b32_dpp v11, v4 quad_perm:[1,0,3,2] row_mask:0xf bank_mask:0xf
	v_cndmask_b32_e32 v3, v138, v3, vcc
	v_lshlrev_b32_e32 v44, 2, v3
	s_nop 1
	v_mov_b32_dpp v3, v2 quad_perm:[2,3,0,1] row_mask:0xf bank_mask:0xf
	s_waitcnt lgkmcnt(1)
	v_max_f32_e32 v11, v11, v11
	v_max_f32_e32 v4, v4, v11
	s_nop 1
	v_mov_b32_dpp v11, v4 quad_perm:[2,3,0,1] row_mask:0xf bank_mask:0xf
	s_waitcnt lgkmcnt(1)
	v_max_f32_e32 v3, v3, v3
	v_min_f32_e32 v2, v2, v3
	v_xor_b32_e32 v3, 4, v138
	v_cmp_lt_i32_e32 vcc, v3, v5
	s_waitcnt lgkmcnt(0)
	v_max_f32_e32 v11, v11, v11
	v_max_f32_e32 v4, v4, v11
	v_cndmask_b32_e32 v3, v138, v3, vcc
	v_lshlrev_b32_e32 v45, 2, v3
	s_nop 1
	v_mov_b32_dpp v3, v2 row_shl:4 row_mask:0xf bank_mask:0x5
	s_nop 1
	v_mov_b32_dpp v3, v2 row_shr:4 row_mask:0xf bank_mask:0xa
	s_nop 1
	v_mov_b32_dpp v11, v4 row_shl:4 row_mask:0xf bank_mask:0x5
	s_nop 1
	v_mov_b32_dpp v11, v4 row_shr:4 row_mask:0xf bank_mask:0xa
	s_waitcnt lgkmcnt(1)
	v_max_f32_e32 v3, v3, v3
	v_min_f32_e32 v2, v2, v3
	v_xor_b32_e32 v3, 8, v138
	v_cmp_lt_i32_e32 vcc, v3, v5
	s_waitcnt lgkmcnt(0)
	v_max_f32_e32 v11, v11, v11
	v_max_f32_e32 v4, v4, v11
	v_cndmask_b32_e32 v3, v138, v3, vcc
	v_lshlrev_b32_e32 v46, 2, v3
	s_nop 1
	v_mov_b32_dpp v3, v2 row_ror:8 row_mask:0xf bank_mask:0xf
	s_nop 1
	v_mov_b32_dpp v11, v4 row_ror:8 row_mask:0xf bank_mask:0xf
	s_waitcnt lgkmcnt(1)
	v_max_f32_e32 v3, v3, v3
	v_min_f32_e32 v2, v2, v3
	v_xor_b32_e32 v3, 16, v138
	v_cmp_lt_i32_e32 vcc, v3, v5
	s_waitcnt lgkmcnt(0)
	v_max_f32_e32 v11, v11, v11
	v_max_f32_e32 v4, v4, v11
	v_cndmask_b32_e32 v3, v138, v3, vcc
	v_lshlrev_b32_e32 v5, 2, v3
	v_mov_b32_e32 v3, v2
	v_mov_b32_e32 v253, v2
	s_nop 1
	v_permlane16_swap_b32_e32 v3, v253
	v_cndmask_b32_e64 v3, v3, v253, s[100:101]
	v_mov_b32_e32 v5, v4
	v_mov_b32_e32 v253, v4
	s_nop 1
	v_permlane16_swap_b32_e32 v5, v253
	v_cndmask_b32_e64 v5, v5, v253, s[100:101]
	v_cmp_eq_u32_e32 vcc, 0, v8
	s_and_saveexec_b64 s[0:1], vcc
	s_cbranch_execz .LBB0_505
	s_waitcnt lgkmcnt(1)
	v_max_f32_e32 v3, v3, v3
	v_max_f32_e32 v2, v2, v2
	v_readlane_b32 s3, v255, 2
	s_waitcnt lgkmcnt(0)
	v_max_f32_e32 v5, v5, v5
	v_max_f32_e32 v4, v4, v4
	v_min_f32_e32 v2, v2, v3
	v_mov_b32_e32 v3, s3
	v_max_f32_e32 v4, v4, v5
	v_add_u32_e32 v3, 0x9800, v3
	ds_write2_b32 v3, v2, v4 offset0:128 offset1:136
